# l5 state scan: waves 2-3 act as prefetch helpers (issue the scanner waves' Bc loads 3 batches ahead into L2)
# baseline (speedup 1.0000x reference)
; DI unsigned pk2(float a, float b) { f32x2 v; v[0] = a; v[1] = b; return __builtin_bit_cast(unsigned, __builtin_convertvector(v, bf16v2)); }
; DI void phase_l5(const P& p, int layer, float* ldsf) {
;     ...
;       for (int idx4 = bid_ * 128 + tid; idx4 < 8 * 4096; idx4 += gridDim.x * 128) {
;         const int g = idx4 >> 12, ed = (idx4 & 4095) * 4, d = ed & 127;
;         float s0 = 0.f, s1 = 0.f, s2 = 0.f, s3 = 0.f;
; #pragma unroll 1
;         for (int c0 = 0; c0 < 256; c0 += 16) {
;           float4 av[16]; u32x2 bv[16];
; #pragma unroll
;           for (int k = 0; k < 16; ++k) {
;             av[k] = *reinterpret_cast<const float4*>(adec + ((c0 + k) * 8 + g) * 128 + d);
;             bv[k] = *reinterpret_cast<const u32x2*>(Bc + (long)((c0 + k) * 8 + g) * 16384 + ed);
;           }
; #pragma unroll
;           for (int k = 0; k < 16; ++k) {
;             u32x2 so; so[0] = pk2(s0, s1); so[1] = pk2(s2, s3);
;             *reinterpret_cast<u32x2*>(Sst + (long)((c0 + k) * 8 + g) * 16384 + ed) = so;
;             s0 = av[k].x * s0 + __uint_as_float(bv[k][0] << 16); s1 = av[k].y * s1 + __uint_as_float(bv[k][0] & 0xffff0000u);
;             s2 = av[k].z * s2 + __uint_as_float(bv[k][1] << 16); s3 = av[k].w * s3 + __uint_as_float(bv[k][1] & 0xffff0000u);
;           }
;         }
.LBB0_292:
	v_lshl_add_u64 v[10:11], s[46:47], 0, v[2:3]
	v_add_co_u32_e32 v12, vcc, 0x24f00000, v10
	v_lshl_add_u64 v[14:15], s[46:47], 0, v[4:5]
	s_nop 0
	v_addc_co_u32_e32 v13, vcc, 0, v11, vcc
	global_load_dwordx2 v[44:45], v[12:13], off
	v_add_co_u32_e32 v12, vcc, 0x24f40000, v10
	s_mov_b32 s7, 0x24e01000
	s_nop 0
	v_addc_co_u32_e32 v13, vcc, 0, v11, vcc
	global_load_dwordx2 v[36:37], v[12:13], off
	v_add_co_u32_e32 v12, vcc, 0x24f80000, v10
	v_cvt_pk_bf16_f32 v46, v6, v7
	s_nop 0
	v_addc_co_u32_e32 v13, vcc, 0, v11, vcc
	global_load_dwordx2 v[38:39], v[12:13], off
	v_add_co_u32_e32 v12, vcc, 0x24fc0000, v10
	v_cvt_pk_bf16_f32 v47, v8, v9
	s_nop 0
	v_addc_co_u32_e32 v13, vcc, 0, v11, vcc
	global_load_dwordx2 v[40:41], v[12:13], off
	v_add_co_u32_e32 v12, vcc, 0x25000000, v10
	s_mov_b64 s[8:9], 0x400000
	s_nop 0
	v_addc_co_u32_e32 v13, vcc, 0, v11, vcc
	global_load_dwordx2 v[42:43], v[12:13], off
	v_add_co_u32_e32 v12, vcc, 0x25040000, v10
	s_add_i32 s6, s6, 16
	s_nop 0
	v_addc_co_u32_e32 v13, vcc, 0, v11, vcc
	global_load_dwordx2 v[34:35], v[12:13], off
	v_add_co_u32_e32 v12, vcc, 0x25080000, v10
	v_lshl_add_u64 v[2:3], v[2:3], 0, s[8:9]
	s_nop 0
	v_addc_co_u32_e32 v13, vcc, 0, v11, vcc
	global_load_dwordx2 v[22:23], v[12:13], off
	v_add_co_u32_e32 v12, vcc, 0x250c0000, v10
	s_mov_b64 s[8:9], 0x10000
	s_nop 0
	v_addc_co_u32_e32 v13, vcc, 0, v11, vcc
	global_load_dwordx2 v[24:25], v[12:13], off
	v_add_co_u32_e32 v12, vcc, 0x25100000, v10
	v_lshl_add_u64 v[4:5], v[4:5], 0, s[8:9]
	s_nop 0
	v_addc_co_u32_e32 v13, vcc, 0, v11, vcc
	global_load_dwordx2 v[26:27], v[12:13], off
	v_add_co_u32_e32 v12, vcc, 0x25140000, v10
	s_cmpk_gt_u32 s6, 0xef
	s_nop 0
	v_addc_co_u32_e32 v13, vcc, 0, v11, vcc
	global_load_dwordx2 v[28:29], v[12:13], off
	v_add_co_u32_e32 v12, vcc, 0x25180000, v10
	s_waitcnt vmcnt(9)
	v_lshlrev_b32_e32 v48, 16, v44
	v_addc_co_u32_e32 v13, vcc, 0, v11, vcc
	global_load_dwordx2 v[30:31], v[12:13], off
	v_add_co_u32_e32 v12, vcc, 0x251c0000, v10
	v_and_b32_e32 v49, 0xffff0000, v44
	s_nop 0
	v_addc_co_u32_e32 v13, vcc, 0, v11, vcc
	global_load_dwordx2 v[32:33], v[12:13], off
	v_add_co_u32_e32 v12, vcc, 0x25200000, v10
	v_lshlrev_b32_e32 v72, 16, v45
	s_nop 0
	v_addc_co_u32_e32 v13, vcc, 0, v11, vcc
	global_load_dwordx2 v[16:17], v[12:13], off
	v_add_co_u32_e32 v12, vcc, 0x25240000, v10
	v_and_b32_e32 v73, 0xffff0000, v45
	s_nop 0
	v_addc_co_u32_e32 v13, vcc, 0, v11, vcc
	global_load_dwordx2 v[18:19], v[12:13], off
	v_add_co_u32_e32 v12, vcc, 0x25280000, v10
	s_waitcnt vmcnt(8)
	v_lshlrev_b32_e32 v76, 16, v34
	v_addc_co_u32_e32 v13, vcc, 0, v11, vcc
	global_load_dwordx2 v[20:21], v[12:13], off
	v_add_co_u32_e32 v12, vcc, 0x252c0000, v10
	v_and_b32_e32 v77, 0xffff0000, v34
	s_nop 0
	v_addc_co_u32_e32 v13, vcc, 0, v11, vcc
	v_add_co_u32_e32 v44, vcc, s7, v14
	s_mov_b32 s7, 0x24e03000
	s_nop 0
	v_addc_co_u32_e32 v45, vcc, 0, v15, vcc
	global_load_dwordx2 v[12:13], v[12:13], off
	s_nop 0
	global_load_dwordx4 v[52:55], v[44:45], off offset:-4096
	global_load_dwordx4 v[56:59], v[44:45], off
	v_add_co_u32_e32 v44, vcc, s7, v14
	s_mov_b32 s7, 0x24e05000
	s_nop 0
	v_addc_co_u32_e32 v45, vcc, 0, v15, vcc
	v_add_co_u32_e32 v74, vcc, s7, v14
	global_load_dwordx4 v[60:63], v[44:45], off offset:-4096
	global_load_dwordx4 v[64:67], v[44:45], off
	v_addc_co_u32_e32 v75, vcc, 0, v15, vcc
	global_load_dwordx4 v[68:71], v[74:75], off offset:-4096
	v_lshlrev_b32_e32 v44, 16, v36
	v_and_b32_e32 v45, 0xffff0000, v36
	s_mov_b32 s7, 0x24e07000
	v_lshlrev_b32_e32 v34, 16, v35
	v_and_b32_e32 v35, 0xffff0000, v35
	s_waitcnt vmcnt(10)
	v_lshlrev_b32_e32 v78, 16, v30
	v_and_b32_e32 v79, 0xffff0000, v30
	v_lshlrev_b32_e32 v82, 16, v31
	v_and_b32_e32 v83, 0xffff0000, v31
	s_waitcnt vmcnt(4)
	v_pk_fma_f32 v[6:7], v[6:7], v[52:53], v[48:49]
	s_nop 0
	v_cvt_pk_bf16_f32 v48, v6, v7
	s_waitcnt vmcnt(3)
	v_pk_fma_f32 v[6:7], v[56:57], v[6:7], v[44:45]
	v_lshlrev_b32_e32 v52, 16, v38
	v_and_b32_e32 v53, 0xffff0000, v38
	v_cvt_pk_bf16_f32 v44, v6, v7
	v_pk_fma_f32 v[8:9], v[8:9], v[54:55], v[72:73]
	v_add_co_u32_e32 v56, vcc, s7, v14
	s_waitcnt vmcnt(2)
	v_pk_fma_f32 v[6:7], v[60:61], v[6:7], v[52:53]
	v_lshlrev_b32_e32 v52, 16, v40
	v_and_b32_e32 v53, 0xffff0000, v40
	v_cvt_pk_bf16_f32 v38, v6, v7
	s_waitcnt vmcnt(1)
	v_pk_fma_f32 v[6:7], v[64:65], v[6:7], v[52:53]
	v_lshlrev_b32_e32 v52, 16, v42
	v_and_b32_e32 v53, 0xffff0000, v42
	v_cvt_pk_bf16_f32 v36, v6, v7
	s_waitcnt vmcnt(0)
	v_pk_fma_f32 v[6:7], v[68:69], v[6:7], v[52:53]
	v_lshlrev_b32_e32 v52, 16, v37
	v_and_b32_e32 v53, 0xffff0000, v37
	v_cvt_pk_bf16_f32 v49, v8, v9
	v_pk_fma_f32 v[8:9], v[58:59], v[8:9], v[52:53]
	v_lshlrev_b32_e32 v52, 16, v39
	v_and_b32_e32 v53, 0xffff0000, v39
	v_cvt_pk_bf16_f32 v45, v8, v9
	v_pk_fma_f32 v[8:9], v[62:63], v[8:9], v[52:53]
	v_lshlrev_b32_e32 v40, 16, v41
	v_and_b32_e32 v41, 0xffff0000, v41
	v_cvt_pk_bf16_f32 v39, v8, v9
	v_pk_fma_f32 v[8:9], v[66:67], v[8:9], v[40:41]
	v_lshlrev_b32_e32 v40, 16, v43
	v_and_b32_e32 v41, 0xffff0000, v43
	v_pk_fma_f32 v[72:73], v[70:71], v[8:9], v[40:41]
	global_load_dwordx4 v[40:43], v[74:75], off
	v_addc_co_u32_e32 v57, vcc, 0, v15, vcc
	s_mov_b32 s7, 0x24e09000
	global_load_dwordx4 v[52:55], v[56:57], off offset:-4096
	s_nop 0
	global_load_dwordx4 v[56:59], v[56:57], off
	v_add_co_u32_e32 v64, vcc, s7, v14
	v_cvt_pk_bf16_f32 v37, v8, v9
	s_nop 0
	v_addc_co_u32_e32 v65, vcc, 0, v15, vcc
	global_load_dwordx4 v[60:63], v[64:65], off offset:-4096
	s_nop 0
	global_load_dwordx4 v[64:67], v[64:65], off
	v_cvt_pk_bf16_f32 v8, v6, v7
	s_mov_b32 s7, 0x24e0b000
	v_add_co_u32_e32 v74, vcc, s7, v14
	s_mov_b32 s7, 0x24e0d000
	s_nop 0
	v_addc_co_u32_e32 v75, vcc, 0, v15, vcc
	global_load_dwordx4 v[68:71], v[74:75], off offset:-4096
	v_add_co_u32_e32 v30, vcc, s7, v14
	s_mov_b32 s7, 0x24e0f000
	s_nop 0
	v_addc_co_u32_e32 v31, vcc, 0, v15, vcc
	v_add_co_u32_e32 v14, vcc, s7, v14
	s_mov_b32 s7, 0x2cf00000
	s_nop 0
	v_addc_co_u32_e32 v15, vcc, 0, v15, vcc
	v_cvt_pk_bf16_f32 v9, v72, v73
	s_waitcnt vmcnt(5)
; DI unsigned pk2(float a, float b) { f32x2 v; v[0] = a; v[1] = b; return __builtin_bit_cast(unsigned, __builtin_convertvector(v, bf16v2)); }
; DI void phase_l5(const P& p, int layer, float* ldsf) {
;     ...
; #pragma unroll
;           for (int k = 0; k < 16; ++k) {
;             u32x2 so; so[0] = pk2(s0, s1); so[1] = pk2(s2, s3);
;             *reinterpret_cast<u32x2*>(Sst + (long)((c0 + k) * 8 + g) * 16384 + ed) = so;
;             s0 = av[k].x * s0 + __uint_as_float(bv[k][0] << 16); s1 = av[k].y * s1 + __uint_as_float(bv[k][0] & 0xffff0000u);
;             s2 = av[k].z * s2 + __uint_as_float(bv[k][1] << 16); s3 = av[k].w * s3 + __uint_as_float(bv[k][1] & 0xffff0000u);
;           }
;         }
	v_pk_fma_f32 v[6:7], v[40:41], v[6:7], v[76:77]
	v_lshlrev_b32_e32 v40, 16, v22
	v_and_b32_e32 v41, 0xffff0000, v22
	v_pk_fma_f32 v[34:35], v[42:43], v[72:73], v[34:35]
	v_lshlrev_b32_e32 v22, 16, v23
	v_and_b32_e32 v23, 0xffff0000, v23
	v_cvt_pk_bf16_f32 v76, v6, v7
	s_waitcnt vmcnt(4)
	v_pk_fma_f32 v[6:7], v[52:53], v[6:7], v[40:41]
	v_lshlrev_b32_e32 v40, 16, v24
	v_and_b32_e32 v41, 0xffff0000, v24
	v_pk_fma_f32 v[22:23], v[54:55], v[34:35], v[22:23]
	v_lshlrev_b32_e32 v24, 16, v25
	v_and_b32_e32 v25, 0xffff0000, v25
	v_cvt_pk_bf16_f32 v81, v22, v23
	s_waitcnt vmcnt(3)
	v_pk_fma_f32 v[22:23], v[58:59], v[22:23], v[24:25]
	v_lshlrev_b32_e32 v24, 16, v27
	v_and_b32_e32 v25, 0xffff0000, v27
	v_cvt_pk_bf16_f32 v80, v6, v7
	v_pk_fma_f32 v[6:7], v[56:57], v[6:7], v[40:41]
	v_lshlrev_b32_e32 v40, 16, v26
	v_and_b32_e32 v41, 0xffff0000, v26
	v_cvt_pk_bf16_f32 v57, v22, v23
	s_waitcnt vmcnt(2)
	v_pk_fma_f32 v[22:23], v[62:63], v[22:23], v[24:25]
	v_lshlrev_b32_e32 v24, 16, v29
	v_and_b32_e32 v25, 0xffff0000, v29
	v_cvt_pk_bf16_f32 v56, v6, v7
	v_pk_fma_f32 v[6:7], v[60:61], v[6:7], v[40:41]
	v_cvt_pk_bf16_f32 v77, v34, v35
	v_cvt_pk_bf16_f32 v61, v22, v23
	s_waitcnt vmcnt(1)
	v_pk_fma_f32 v[34:35], v[66:67], v[22:23], v[24:25]
	global_load_dwordx4 v[22:25], v[74:75], off
	v_lshlrev_b32_e32 v40, 16, v28
	v_and_b32_e32 v41, 0xffff0000, v28
	v_lshlrev_b32_e32 v58, 16, v32
	v_and_b32_e32 v59, 0xffff0000, v32
	v_lshlrev_b32_e32 v62, 16, v33
	v_and_b32_e32 v63, 0xffff0000, v33
	global_load_dwordx4 v[26:29], v[30:31], off offset:-4096
	s_nop 0
	global_load_dwordx4 v[30:33], v[30:31], off
	v_cvt_pk_bf16_f32 v60, v6, v7
	v_pk_fma_f32 v[6:7], v[64:65], v[6:7], v[40:41]
	global_load_dwordx4 v[40:43], v[14:15], off offset:-4096
	global_load_dwordx4 v[52:55], v[14:15], off
	v_cvt_pk_bf16_f32 v64, v6, v7
	s_waitcnt vmcnt(5)
	v_pk_fma_f32 v[6:7], v[68:69], v[6:7], v[78:79]
	v_cvt_pk_bf16_f32 v65, v34, v35
	v_cvt_pk_bf16_f32 v14, v6, v7
	s_waitcnt vmcnt(4)
	v_pk_fma_f32 v[6:7], v[22:23], v[6:7], v[58:59]
	v_lshlrev_b32_e32 v58, 16, v16
	v_and_b32_e32 v59, 0xffff0000, v16
	v_cvt_pk_bf16_f32 v22, v6, v7
	s_waitcnt vmcnt(3)
	v_pk_fma_f32 v[6:7], v[26:27], v[6:7], v[58:59]
	v_lshlrev_b32_e32 v26, 16, v18
	v_and_b32_e32 v27, 0xffff0000, v18
	v_cvt_pk_bf16_f32 v16, v6, v7
	s_waitcnt vmcnt(2)
	v_pk_fma_f32 v[6:7], v[30:31], v[6:7], v[26:27]
	v_lshlrev_b32_e32 v26, 16, v20
	v_and_b32_e32 v27, 0xffff0000, v20
	v_cvt_pk_bf16_f32 v18, v6, v7
	s_waitcnt vmcnt(1)
	v_pk_fma_f32 v[6:7], v[40:41], v[6:7], v[26:27]
	v_lshlrev_b32_e32 v26, 16, v12
	v_and_b32_e32 v27, 0xffff0000, v12
	v_cvt_pk_bf16_f32 v20, v6, v7
	s_waitcnt vmcnt(0)
	v_pk_fma_f32 v[6:7], v[52:53], v[6:7], v[26:27]
	v_pk_fma_f32 v[26:27], v[70:71], v[34:35], v[82:83]
	s_nop 0
	v_cvt_pk_bf16_f32 v15, v26, v27
	v_pk_fma_f32 v[24:25], v[24:25], v[26:27], v[62:63]
	v_lshlrev_b32_e32 v26, 16, v17
	v_and_b32_e32 v27, 0xffff0000, v17
	v_cvt_pk_bf16_f32 v23, v24, v25
	v_pk_fma_f32 v[24:25], v[28:29], v[24:25], v[26:27]
	v_lshlrev_b32_e32 v26, 16, v19
	v_and_b32_e32 v27, 0xffff0000, v19
	v_cvt_pk_bf16_f32 v17, v24, v25
	v_pk_fma_f32 v[24:25], v[32:33], v[24:25], v[26:27]
	v_lshlrev_b32_e32 v26, 16, v21
	v_and_b32_e32 v27, 0xffff0000, v21
	v_cvt_pk_bf16_f32 v19, v24, v25
	v_pk_fma_f32 v[24:25], v[42:43], v[24:25], v[26:27]
	v_add_co_u32_e32 v26, vcc, s7, v10
	s_mov_b32 s7, 0x2cf40000
	s_nop 0
	v_addc_co_u32_e32 v27, vcc, 0, v11, vcc
	global_store_dwordx2 v[26:27], v[46:47], off
	v_add_co_u32_e32 v26, vcc, s7, v10
	s_mov_b32 s7, 0x2cf80000
	s_nop 0
	v_addc_co_u32_e32 v27, vcc, 0, v11, vcc
	global_store_dwordx2 v[26:27], v[48:49], off
	v_add_co_u32_e32 v26, vcc, s7, v10
	s_mov_b32 s7, 0x2cfc0000
	s_nop 0
	v_addc_co_u32_e32 v27, vcc, 0, v11, vcc
	global_store_dwordx2 v[26:27], v[44:45], off
	v_add_co_u32_e32 v26, vcc, s7, v10
	s_mov_b32 s7, 0x2d000000
	s_nop 0
	v_addc_co_u32_e32 v27, vcc, 0, v11, vcc
	global_store_dwordx2 v[26:27], v[38:39], off
	v_add_co_u32_e32 v26, vcc, s7, v10
	s_mov_b32 s7, 0x2d040000
	s_nop 0
	v_addc_co_u32_e32 v27, vcc, 0, v11, vcc
	global_store_dwordx2 v[26:27], v[36:37], off
	v_add_co_u32_e32 v26, vcc, s7, v10
	s_mov_b32 s7, 0x2d080000
	s_nop 0
	v_addc_co_u32_e32 v27, vcc, 0, v11, vcc
	global_store_dwordx2 v[26:27], v[8:9], off
	v_add_co_u32_e32 v8, vcc, s7, v10
	s_mov_b32 s7, 0x2d0c0000
	s_nop 0
	v_addc_co_u32_e32 v9, vcc, 0, v11, vcc
	global_store_dwordx2 v[8:9], v[76:77], off
	v_add_co_u32_e32 v8, vcc, s7, v10
	s_mov_b32 s7, 0x2d100000
	s_nop 0
	v_addc_co_u32_e32 v9, vcc, 0, v11, vcc
	global_store_dwordx2 v[8:9], v[80:81], off
	v_add_co_u32_e32 v8, vcc, s7, v10
	s_mov_b32 s7, 0x2d140000
	s_nop 0
	v_addc_co_u32_e32 v9, vcc, 0, v11, vcc
	global_store_dwordx2 v[8:9], v[56:57], off
	v_add_co_u32_e32 v8, vcc, s7, v10
	s_mov_b32 s7, 0x2d180000
	s_nop 0
	v_addc_co_u32_e32 v9, vcc, 0, v11, vcc
	global_store_dwordx2 v[8:9], v[60:61], off
	v_add_co_u32_e32 v8, vcc, s7, v10
	s_mov_b32 s7, 0x2d1c0000
	s_nop 0
	v_addc_co_u32_e32 v9, vcc, 0, v11, vcc
	global_store_dwordx2 v[8:9], v[64:65], off
	v_add_co_u32_e32 v8, vcc, s7, v10
	s_mov_b32 s7, 0x2d200000
	s_nop 0
	v_addc_co_u32_e32 v9, vcc, 0, v11, vcc
	global_store_dwordx2 v[8:9], v[14:15], off
	v_add_co_u32_e32 v8, vcc, s7, v10
	s_mov_b32 s7, 0x2d240000
	s_nop 0
	v_addc_co_u32_e32 v9, vcc, 0, v11, vcc
	global_store_dwordx2 v[8:9], v[22:23], off
	v_add_co_u32_e32 v8, vcc, s7, v10
	s_mov_b32 s7, 0x2d280000
	s_nop 0
	v_addc_co_u32_e32 v9, vcc, 0, v11, vcc
	global_store_dwordx2 v[8:9], v[16:17], off
	v_add_co_u32_e32 v8, vcc, s7, v10
	s_mov_b32 s7, 0x2d2c0000
	s_nop 0
	v_addc_co_u32_e32 v9, vcc, 0, v11, vcc
	global_store_dwordx2 v[8:9], v[18:19], off
	v_add_co_u32_e32 v8, vcc, s7, v10
	v_cvt_pk_bf16_f32 v21, v24, v25
	s_nop 0
	v_addc_co_u32_e32 v9, vcc, 0, v11, vcc
	global_store_dwordx2 v[8:9], v[20:21], off
	v_lshlrev_b32_e32 v8, 16, v13
	v_and_b32_e32 v9, 0xffff0000, v13
	v_pk_fma_f32 v[8:9], v[54:55], v[24:25], v[8:9]
	s_cbranch_scc0 .LBB0_292
	v_add_u32_e32 v50, s2, v50
	v_cmp_lt_i32_e32 vcc, s75, v50
	s_or_b64 s[4:5], vcc, s[4:5]
	v_add_u32_e32 v51, s3, v51
	s_andn2_b64 exec, exec, s[4:5]
	s_cbranch_execnz .LBB0_291
	s_branch .LBB0_294
; DI void phase_l5(const P& p, int layer, float* ldsf) {
;     ...
;       for (int idx4 = bid_ * 128 + tid; idx4 < 8 * 4096; idx4 += gridDim.x * 128) {
;         const int g = idx4 >> 12, ed = (idx4 & 4095) * 4, d = ed & 127;
;         float s0 = 0.f, s1 = 0.f, s2 = 0.f, s3 = 0.f;
; #pragma unroll 1
;         for (int c0 = 0; c0 < 256; c0 += 16) {
;           float4 av[16]; u32x2 bv[16];
; #pragma unroll
;           for (int k = 0; k < 16; ++k) {
;             av[k] = *reinterpret_cast<const float4*>(adec + ((c0 + k) * 8 + g) * 128 + d);
;             bv[k] = *reinterpret_cast<const u32x2*>(Bc + (long)((c0 + k) * 8 + g) * 16384 + ed);
;           }
.Lscan_helper:
	s_mov_b64 exec, s[0:1]
	v_readfirstlane_b32 s2, v0
	s_lshr_b32 s2, s2, 7
	s_cmp_lg_u32 s2, 1
	s_cbranch_scc1 .LBB0_294
	v_add_u32_e32 v2, 0xffffff80, v0
	v_lshl_add_u32 v2, s36, 7, v2
	v_ashrrev_i32_e32 v3, 12, v2
	v_lshlrev_b32_e32 v3, 15, v3
	v_and_b32_e32 v2, 0xfff, v2
	v_lshl_or_b32 v2, v2, 3, v3
	v_mov_b32_e32 v3, 0
	v_lshl_add_u64 v[2:3], s[46:47], 0, v[2:3]
	v_add_co_u32_e32 v2, vcc, 0x24f00000, v2
	s_nop 1
	v_addc_co_u32_e32 v3, vcc, 0, v3, vcc
	s_mov_b32 s2, 0
.Lscan_helper_loop:
	global_load_dwordx2 v[10:11], v[2:3], off
	v_add_co_u32_e32 v4, vcc, 0x40000, v2
	s_nop 1
	v_addc_co_u32_e32 v5, vcc, 0, v3, vcc
	global_load_dwordx2 v[12:13], v[4:5], off
	v_add_co_u32_e32 v4, vcc, 0x80000, v2
	s_nop 1
	v_addc_co_u32_e32 v5, vcc, 0, v3, vcc
	global_load_dwordx2 v[14:15], v[4:5], off
	v_add_co_u32_e32 v4, vcc, 0xc0000, v2
	s_nop 1
	v_addc_co_u32_e32 v5, vcc, 0, v3, vcc
	global_load_dwordx2 v[16:17], v[4:5], off
	v_add_co_u32_e32 v4, vcc, 0x100000, v2
	s_nop 1
	v_addc_co_u32_e32 v5, vcc, 0, v3, vcc
	global_load_dwordx2 v[18:19], v[4:5], off
	v_add_co_u32_e32 v4, vcc, 0x140000, v2
	s_nop 1
	v_addc_co_u32_e32 v5, vcc, 0, v3, vcc
	global_load_dwordx2 v[20:21], v[4:5], off
	v_add_co_u32_e32 v4, vcc, 0x180000, v2
	s_nop 1
	v_addc_co_u32_e32 v5, vcc, 0, v3, vcc
	global_load_dwordx2 v[22:23], v[4:5], off
	v_add_co_u32_e32 v4, vcc, 0x1c0000, v2
	s_nop 1
	v_addc_co_u32_e32 v5, vcc, 0, v3, vcc
	global_load_dwordx2 v[24:25], v[4:5], off
	v_add_co_u32_e32 v4, vcc, 0x200000, v2
	s_nop 1
	v_addc_co_u32_e32 v5, vcc, 0, v3, vcc
	global_load_dwordx2 v[26:27], v[4:5], off
	v_add_co_u32_e32 v4, vcc, 0x240000, v2
	s_nop 1
	v_addc_co_u32_e32 v5, vcc, 0, v3, vcc
	global_load_dwordx2 v[28:29], v[4:5], off
	v_add_co_u32_e32 v4, vcc, 0x280000, v2
	s_nop 1
	v_addc_co_u32_e32 v5, vcc, 0, v3, vcc
	global_load_dwordx2 v[30:31], v[4:5], off
	v_add_co_u32_e32 v4, vcc, 0x2c0000, v2
	s_nop 1
	v_addc_co_u32_e32 v5, vcc, 0, v3, vcc
	global_load_dwordx2 v[32:33], v[4:5], off
	v_add_co_u32_e32 v4, vcc, 0x300000, v2
	s_nop 1
	v_addc_co_u32_e32 v5, vcc, 0, v3, vcc
	global_load_dwordx2 v[34:35], v[4:5], off
	v_add_co_u32_e32 v4, vcc, 0x340000, v2
	s_nop 1
	v_addc_co_u32_e32 v5, vcc, 0, v3, vcc
	global_load_dwordx2 v[36:37], v[4:5], off
	v_add_co_u32_e32 v4, vcc, 0x380000, v2
	s_nop 1
	v_addc_co_u32_e32 v5, vcc, 0, v3, vcc
	global_load_dwordx2 v[38:39], v[4:5], off
	v_add_co_u32_e32 v4, vcc, 0x3c0000, v2
	s_nop 1
	v_addc_co_u32_e32 v5, vcc, 0, v3, vcc
	global_load_dwordx2 v[40:41], v[4:5], off
	s_waitcnt vmcnt(32)
	v_add_co_u32_e32 v2, vcc, 0x400000, v2
	s_nop 1
	v_addc_co_u32_e32 v3, vcc, 0, v3, vcc
	s_add_i32 s2, s2, 1
	s_cmp_lt_u32 s2, 16
	s_cbranch_scc1 .Lscan_helper_loop
	s_waitcnt vmcnt(0)
